# P1: waves 1-7 issue the loads of their first four input rows while parked at grid barrier 1 (inputs do not depend on P0); row loop copies instead of loading on its first pass
# baseline (speedup 1.0000x reference)
; __device__ __forceinline__ void xcd_barrier(const XcdBarrier& b) {
;     ...
;     if (threadIdx.x == 0) {
;         unsigned* bar = b.bar;
;         __builtin_amdgcn_s_waitcnt(0);
;         unsigned nloc = b.st[0], nx = b.st[1];
;         if (nloc == 0u) { xcd_barrier_complete(bar, b.x, nloc, nx); b.st[0] = nloc; b.st[1] = nx; }
; __global__ void __launch_bounds__(NT, 2) fwd_kernel(Args args) {
;     ...
;             for (int q = 0; q < 4; ++q) { if (q < nr) { const float* src = (grp < 2) ? x + (size_t)(64 * bl + 8 * wave + 4 * grp + q) * D : ctx + (size_t)(4 * bl + wave) * D;
; #pragma unroll
;                 for (int j = 0; j < 4; ++j) v[q][j] = *(const f32x4*)(src + 4 * (lane + 64 * j)); } }
.LBB0_45:
	s_waitcnt vmcnt(0)
	s_waitcnt lgkmcnt(0)
	s_barrier
	v_readfirstlane_b32 s98, v0
	s_lshr_b32 s98, s98, 6
	s_cmp_eq_u32 s98, 0
	s_cbranch_scc1 .Lp1pf_none
	v_readlane_b32 s100, v240, 11
	v_readlane_b32 s101, v240, 12
	s_lshl_b32 s99, s2, 3
	s_add_u32 s99, s99, s98
	s_lshl_b32 s99, s99, 15
	v_and_b32_e32 v232, 63, v0
	v_lshlrev_b32_e32 v232, 4, v232
	s_add_u32 s100, s100, s99
	s_addc_u32 s101, s101, 0
	global_load_dwordx4 v[168:171], v232, s[100:101] nt
	global_load_dwordx4 v[172:175], v232, s[100:101] offset:1024 nt
	global_load_dwordx4 v[176:179], v232, s[100:101] offset:2048 nt
	global_load_dwordx4 v[180:183], v232, s[100:101] offset:3072 nt
	s_add_u32 s100, s100, 0x1000
	s_addc_u32 s101, s101, 0
	global_load_dwordx4 v[184:187], v232, s[100:101] nt
	global_load_dwordx4 v[188:191], v232, s[100:101] offset:1024 nt
	global_load_dwordx4 v[192:195], v232, s[100:101] offset:2048 nt
	global_load_dwordx4 v[196:199], v232, s[100:101] offset:3072 nt
	s_add_u32 s100, s100, 0x1000
	s_addc_u32 s101, s101, 0
	global_load_dwordx4 v[200:203], v232, s[100:101] nt
	global_load_dwordx4 v[204:207], v232, s[100:101] offset:1024 nt
	global_load_dwordx4 v[208:211], v232, s[100:101] offset:2048 nt
	global_load_dwordx4 v[212:215], v232, s[100:101] offset:3072 nt
	s_add_u32 s100, s100, 0x1000
	s_addc_u32 s101, s101, 0
	global_load_dwordx4 v[216:219], v232, s[100:101] nt
	global_load_dwordx4 v[220:223], v232, s[100:101] offset:1024 nt
	global_load_dwordx4 v[224:227], v232, s[100:101] offset:2048 nt
	global_load_dwordx4 v[228:231], v232, s[100:101] offset:3072 nt
.Lp1pf_none:
	s_mov_b64 s[4:5], exec
	v_readlane_b32 s0, v240, 8
	s_mov_b64 s[72:73], s[16:17]
	v_readlane_b32 s1, v240, 9
	v_writelane_b32 v240, s72, 27
	s_mov_b64 s[74:75], s[20:21]
	s_and_b64 s[0:1], s[4:5], s[0:1]
	v_writelane_b32 v240, s73, 28
	v_writelane_b32 v240, s96, 29
	v_writelane_b32 v240, s74, 30
	s_nop 1
	v_writelane_b32 v240, s75, 31
	s_mov_b64 exec, s[0:1]
	s_cbranch_execz .LBB0_97
	s_add_i32 s0, 0, 0x20160
	v_mov_b32_e32 v1, s0
	s_waitcnt vmcnt(0) expcnt(0) lgkmcnt(0)
	ds_read_b32 v3, v1
	s_add_i32 s0, 0, 0x20164
	v_mov_b32_e32 v1, s0
	ds_read_b32 v1, v1
	s_waitcnt lgkmcnt(1)
	v_cmp_ne_u32_e32 vcc, 0, v3
	s_cbranch_vccnz .LBB0_61
	s_add_u32 s14, s78, 0x4200
	s_addc_u32 s15, s79, 0
	s_add_u32 s18, s78, 0x4400
	s_addc_u32 s19, s79, 0
	s_add_u32 s22, s78, 0x4500
	s_addc_u32 s23, s79, 0
	s_add_u32 s24, s78, 0x4600
	s_addc_u32 s25, s79, 0
	s_add_u32 s56, s78, 0x4700
	s_addc_u32 s57, s79, 0
	s_add_u32 s68, s78, 0x4800
	s_addc_u32 s69, s79, 0
	s_add_u32 s80, s78, 0x4900
	s_addc_u32 s81, s79, 0
	s_add_u32 s82, s78, 0x4a00
	s_addc_u32 s83, s79, 0
	s_add_u32 s84, s78, 0x4b00
	s_addc_u32 s85, s79, 0
	s_add_u32 s86, s78, 0x4c00
	s_addc_u32 s87, s79, 0
	s_add_u32 s88, s78, 0x4d00
	s_addc_u32 s89, s79, 0
	s_add_u32 s90, s78, 0x4e00
	s_addc_u32 s91, s79, 0
	s_add_u32 s92, s78, 0x4f00
	s_addc_u32 s93, s79, 0
	s_add_u32 s94, s78, 0x5000
	s_load_dwordx2 s[0:1], s[74:75], 0xf0
	s_load_dword s3, s[74:75], 0xf8
	s_addc_u32 s95, s79, 0
	s_add_u32 s96, s78, 0x5100
	s_addc_u32 s97, s79, 0
	s_add_u32 s12, s78, 0x5200
	s_waitcnt lgkmcnt(0)
	s_mul_i32 s0, s1, s0
	s_addc_u32 s13, s79, 0
	s_mul_i32 s3, s0, s3
	s_add_u32 s0, s78, 0x5300
	s_addc_u32 s1, s79, 0
	s_mov_b32 s33, 1
	v_mov_b32_e32 v17, 0
	s_branch .LBB0_49

; __global__ void __launch_bounds__(NT, 2) fwd_kernel(Args args) {
;     ...
;             const int nr = (grp < 2) ? 4 : 1, toff = (grp < 2) ? 0 : 2048;
;             f32x4 v[4][4];
; #pragma unroll
;             for (int q = 0; q < 4; ++q) { if (q < nr) { const float* src = (grp < 2) ? x + (size_t)(64 * bl + 8 * wave + 4 * grp + q) * D : ctx + (size_t)(4 * bl + wave) * D;
; #pragma unroll
;                 for (int j = 0; j < 4; ++j) v[q][j] = *(const f32x4*)(src + 4 * (lane + 64 * j)); } }
.LBB0_102:
	s_cmp_eq_u32 s22, 8
	s_cselect_b64 s[4:5], -1, 0
	s_cmp_lg_u32 s22, 8
	s_cselect_b64 s[12:13], -1, 0
	s_and_b64 s[20:21], s[4:5], s[6:7]
	s_mov_b64 s[0:1], -1
	s_and_b64 vcc, exec, s[20:21]
	s_cbranch_vccnz .LBB0_101
	s_add_i32 s20, s27, s22
	v_readlane_b32 s80, v240, 11
	s_ashr_i32 s21, s20, 31
	v_readlane_b32 s81, v240, 12
	s_lshl_b64 s[0:1], s[20:21], 12
	s_mov_b64 s[16:17], s[80:81]
	s_add_u32 s3, s16, s0
	s_addc_u32 s29, s17, s1
	s_and_b64 s[0:1], s[4:5], exec
	s_cselect_b32 s1, s26, s29
	s_cselect_b32 s0, s23, s3
	s_cmp_lg_u32 s98, 0
	s_cbranch_scc1 .Lp1pf_s0
	global_load_dwordx4 v[82:85], v102, s[0:1]
	global_load_dwordx4 v[74:77], v102, s[0:1] offset:1024
	global_load_dwordx4 v[70:73], v102, s[0:1] offset:2048
	global_load_dwordx4 v[66:69], v102, s[0:1] offset:3072
.Lp1pf_s0:
	v_cndmask_b32_e64 v78, 0, 1, s[12:13]
	v_cmp_ne_u32_e64 s[4:5], 1, v78
	s_andn2_b64 vcc, exec, s[12:13]
	v_readlane_b32 s82, v240, 13
	v_readlane_b32 s83, v240, 14
	v_readlane_b32 s84, v240, 15
	v_readlane_b32 s85, v240, 16
	v_readlane_b32 s86, v240, 17
	v_readlane_b32 s87, v240, 18
	v_readlane_b32 s88, v240, 19
	v_readlane_b32 s89, v240, 20
	v_readlane_b32 s90, v240, 21
	v_readlane_b32 s91, v240, 22
	v_readlane_b32 s92, v240, 23
	v_readlane_b32 s93, v240, 24
	v_readlane_b32 s94, v240, 25
	v_readlane_b32 s95, v240, 26
	s_cbranch_vccz .LBB0_109
	s_and_b64 vcc, exec, s[4:5]
	s_cbranch_vccz .LBB0_110

; __global__ void __launch_bounds__(NT, 2) fwd_kernel(Args args) {
;     ...
;             const int nr = (grp < 2) ? 4 : 1, toff = (grp < 2) ? 0 : 2048;
;             f32x4 v[4][4];
; #pragma unroll
;             for (int q = 0; q < 4; ++q) { if (q < nr) { const float* src = (grp < 2) ? x + (size_t)(64 * bl + 8 * wave + 4 * grp + q) * D : ctx + (size_t)(4 * bl + wave) * D;
; #pragma unroll
;                 for (int j = 0; j < 4; ++j) v[q][j] = *(const f32x4*)(src + 4 * (lane + 64 * j)); } }
.LBB0_106:
	s_add_i32 s0, s20, 3
	s_ashr_i32 s1, s0, 31
	s_lshl_b64 s[0:1], s[0:1], 12
	v_lshl_add_u64 v[62:63], v[86:87], 0, s[0:1]
	s_cmp_lg_u32 s98, 0
	s_cbranch_scc1 .Lp1pf_s3
	global_load_dwordx4 v[46:49], v[62:63], off nt
	global_load_dwordx4 v[54:57], v[62:63], off offset:1024 nt
	global_load_dwordx4 v[58:61], v[62:63], off offset:2048 nt
	s_nop 0
	global_load_dwordx4 v[62:65], v[62:63], off offset:3072 nt
.Lp1pf_s3:
	s_mov_b32 s3, 0
	s_mov_b64 s[0:1], s[20:21]
.LBB0_107:
	s_cmp_eq_u32 s98, 0
	s_cbranch_scc1 .Lp1pf_m
	s_waitcnt vmcnt(0)
	v_mov_b64_e32 v[82:83], v[168:169]
	v_mov_b64_e32 v[84:85], v[170:171]
	v_mov_b64_e32 v[74:75], v[172:173]
	v_mov_b64_e32 v[76:77], v[174:175]
	v_mov_b64_e32 v[70:71], v[176:177]
	v_mov_b64_e32 v[72:73], v[178:179]
	v_mov_b64_e32 v[66:67], v[180:181]
	v_mov_b64_e32 v[68:69], v[182:183]
	v_mov_b64_e32 v[18:19], v[184:185]
	v_mov_b64_e32 v[20:21], v[186:187]
	v_mov_b64_e32 v[22:23], v[188:189]
	v_mov_b64_e32 v[24:25], v[190:191]
	v_mov_b64_e32 v[30:31], v[192:193]
	v_mov_b64_e32 v[32:33], v[194:195]
	v_mov_b64_e32 v[38:39], v[196:197]
	v_mov_b64_e32 v[40:41], v[198:199]
	v_mov_b64_e32 v[26:27], v[200:201]
	v_mov_b64_e32 v[28:29], v[202:203]
	v_mov_b64_e32 v[34:35], v[204:205]
	v_mov_b64_e32 v[36:37], v[206:207]
	v_mov_b64_e32 v[42:43], v[208:209]
	v_mov_b64_e32 v[44:45], v[210:211]
	v_mov_b64_e32 v[50:51], v[212:213]
	v_mov_b64_e32 v[52:53], v[214:215]
	v_mov_b64_e32 v[46:47], v[216:217]
	v_mov_b64_e32 v[48:49], v[218:219]
	v_mov_b64_e32 v[54:55], v[220:221]
	v_mov_b64_e32 v[56:57], v[222:223]
	v_mov_b64_e32 v[58:59], v[224:225]
	v_mov_b64_e32 v[60:61], v[226:227]
	v_mov_b64_e32 v[62:63], v[228:229]
	v_mov_b64_e32 v[64:65], v[230:231]
	s_mov_b32 s98, 0

; __global__ void __launch_bounds__(NT, 2) fwd_kernel(Args args) {
;     ...
;             const int nr = (grp < 2) ? 4 : 1, toff = (grp < 2) ? 0 : 2048;
;             f32x4 v[4][4];
; #pragma unroll
;             for (int q = 0; q < 4; ++q) { if (q < nr) { const float* src = (grp < 2) ? x + (size_t)(64 * bl + 8 * wave + 4 * grp + q) * D : ctx + (size_t)(4 * bl + wave) * D;
; #pragma unroll
;                 for (int j = 0; j < 4; ++j) v[q][j] = *(const f32x4*)(src + 4 * (lane + 64 * j)); } }
.LBB0_109:
	s_add_i32 s0, s20, 1
	s_ashr_i32 s1, s0, 31
	s_lshl_b64 s[0:1], s[0:1], 12
	v_lshl_add_u64 v[38:39], v[86:87], 0, s[0:1]
	s_cmp_lg_u32 s98, 0
	s_cbranch_scc1 .Lp1pf_s1
	global_load_dwordx4 v[18:21], v[38:39], off nt
	global_load_dwordx4 v[22:25], v[38:39], off offset:1024 nt
	global_load_dwordx4 v[30:33], v[38:39], off offset:2048 nt
	s_nop 0
	global_load_dwordx4 v[38:41], v[38:39], off offset:3072 nt
.Lp1pf_s1:
	s_and_b64 vcc, exec, s[4:5]
	s_cbranch_vccnz .LBB0_105
.LBB0_110:
	s_add_i32 s0, s20, 2
	s_ashr_i32 s1, s0, 31
	s_lshl_b64 s[0:1], s[0:1], 12
	v_lshl_add_u64 v[50:51], v[86:87], 0, s[0:1]
	s_cmp_lg_u32 s98, 0
	s_cbranch_scc1 .Lp1pf_s2
	global_load_dwordx4 v[26:29], v[50:51], off nt
	global_load_dwordx4 v[34:37], v[50:51], off offset:1024 nt
	global_load_dwordx4 v[42:45], v[50:51], off offset:2048 nt
	s_nop 0
	global_load_dwordx4 v[50:53], v[50:51], off offset:3072 nt
.Lp1pf_s2:
	s_movk_i32 s3, 0x800
	s_and_b64 vcc, exec, s[4:5]
	s_mov_b64 s[0:1], s[14:15]
	s_cbranch_vccz .LBB0_106
	s_branch .LBB0_107
